# natten: previous-step load wait moved to the top of the step, vmcnt(2) ladders dropped, so the next rows K/V prefetch overlaps the step compute
# speedup vs baseline: 1.0187x; 1.0187x over previous
.LBB0_470:
	s_waitcnt vmcnt(0)
	v_med3_u32 v24, s80, 1, 57
	s_min_u32 s66, s80, 53
	v_readfirstlane_b32 s67, v24
	s_sub_i32 s69, s66, s67
	s_add_i32 s87, s67, 7
	s_add_i32 s88, s69, 4
	s_cmp_gt_i32 s69, -4
	s_cselect_b64 s[66:67], -1, 0
	s_cmp_lt_i32 s69, -3
	v_cmp_gt_i32_e32 vcc, s88, v145
	s_cbranch_scc1 .LBB0_480
	s_lshl_b32 s69, s87, 13
	s_add_u32 s70, s20, s69
	s_addc_u32 s71, s21, 0
	s_and_saveexec_b64 s[82:83], vcc
	s_cbranch_execz .LBB0_473
	v_lshl_add_u64 v[12:13], s[70:71], 0, v[188:189]
	global_load_dwordx4 v[12:15], v[12:13], off

.LBB0_478:
	v_lshl_add_u64 v[8:9], s[82:83], 0, v[122:123]
	global_load_dwordx4 v[8:11], v[8:9], off

.LBB0_480:
	v_mov_b64_e32 v[24:25], v[84:85]
	v_mov_b64_e32 v[28:29], v[80:81]
	s_cmp_eq_u32 s34, 0x78000
	v_mov_b64_e32 v[26:27], v[86:87]
	v_mov_b64_e32 v[30:31], v[82:83]
	s_cbranch_scc1 .LBB0_482
	v_lshl_add_u64 v[24:25], v[124:125], 0, s[34:35]
	v_add_co_u32_e32 v24, vcc, 0x10008000, v24
	s_nop 1
	v_addc_co_u32_e32 v25, vcc, 0, v25, vcc
	global_load_dwordx4 v[28:31], v[24:25], off
	s_nop 0
	global_load_dwordx4 v[24:27], v[24:25], off offset:64

.LBB0_491:
	v_lshl_add_u64 v[0:1], s[82:83], 0, v[114:115]
	global_load_dwordx4 v[0:3], v[0:1], off
	s_or_b64 exec, exec, s[84:85]
	v_cmp_gt_i32_e32 vcc, s88, v146
	s_and_saveexec_b64 s[84:85], vcc
	s_cbranch_execz .LBB0_475
.LBB0_492:
	v_lshl_add_u64 v[16:17], s[70:71], 0, v[116:117]
	global_load_dwordx4 v[16:19], v[16:17], off
	s_or_b64 exec, exec, s[84:85]
	s_and_saveexec_b64 s[84:85], vcc
	s_cbranch_execz .LBB0_476
.LBB0_493:
	v_lshl_add_u64 v[4:5], s[82:83], 0, v[118:119]
	global_load_dwordx4 v[4:7], v[4:5], off
	s_or_b64 exec, exec, s[84:85]
	v_cmp_gt_i32_e32 vcc, s88, v147
	s_and_saveexec_b64 s[84:85], vcc
	s_cbranch_execz .LBB0_477
.LBB0_494:
	v_lshl_add_u64 v[20:21], s[70:71], 0, v[120:121]
	global_load_dwordx4 v[20:23], v[20:21], off
	s_or_b64 exec, exec, s[84:85]
	s_and_saveexec_b64 s[70:71], vcc
	s_cbranch_execnz .LBB0_478
	s_branch .LBB0_479
